# XCD leaders no longer bump the unused per-XCD generation word (one atomic round trip less on the last-arriving workgroup of each XCD)
# speedup vs baseline: 1.0043x; 1.0021x over previous
.LBB0_61:
	s_or_b64 exec, exec, s[8:9]
	s_mov_b64 s[8:9], exec
	v_mbcnt_lo_u32_b32 v1, s8, 0
	v_mbcnt_hi_u32_b32 v1, s9, v1
	v_cmp_eq_u32_e32 vcc, 0, v1
	s_waitcnt vmcnt(0)
	s_and_saveexec_b64 s[10:11], vcc
	s_cbranch_execz .LBB0_63
	s_bcnt1_i32_b64 s7, s[8:9]
	v_mov_b32_e32 v1, 0x2000
	v_mov_b32_e32 v2, s7
.LBB0_63:
	s_or_b64 exec, exec, s[10:11]
	s_waitcnt vmcnt(0)

.LBB0_168:
	s_or_b64 exec, exec, s[4:5]
	s_mov_b64 s[4:5], exec
	v_mbcnt_lo_u32_b32 v2, s4, 0
	v_mbcnt_hi_u32_b32 v2, s5, v2
	v_cmp_eq_u32_e32 vcc, 0, v2
	s_waitcnt vmcnt(0)
	s_and_saveexec_b64 s[6:7], vcc
	s_cbranch_execz .LBB0_170
	s_bcnt1_i32_b64 s4, s[4:5]
	v_mov_b32_e32 v2, 0x2000
	v_mov_b32_e32 v3, s4
.LBB0_170:
	s_or_b64 exec, exec, s[6:7]
	s_waitcnt vmcnt(0)

.LBB0_292:
	s_or_b64 exec, exec, s[4:5]
	s_mov_b64 s[4:5], exec
	v_mbcnt_lo_u32_b32 v2, s4, 0
	v_mbcnt_hi_u32_b32 v2, s5, v2
	v_cmp_eq_u32_e32 vcc, 0, v2
	s_waitcnt vmcnt(0)
	s_and_saveexec_b64 s[6:7], vcc
	s_cbranch_execz .LBB0_294
	s_bcnt1_i32_b64 s4, s[4:5]
	v_mov_b32_e32 v2, 0x2000
	v_mov_b32_e32 v3, s4
.LBB0_294:
	s_or_b64 exec, exec, s[6:7]
	s_waitcnt vmcnt(0)

.LBB0_477:
	s_or_b64 exec, exec, s[4:5]
	s_mov_b64 s[4:5], exec
	v_mbcnt_lo_u32_b32 v2, s4, 0
	v_mbcnt_hi_u32_b32 v2, s5, v2
	v_cmp_eq_u32_e32 vcc, 0, v2
	s_waitcnt vmcnt(0)
	s_and_saveexec_b64 s[6:7], vcc
	s_cbranch_execz .LBB0_479
	s_bcnt1_i32_b64 s4, s[4:5]
	v_mov_b32_e32 v2, 0x2000
	v_mov_b32_e32 v3, s4
.LBB0_479:
	s_or_b64 exec, exec, s[6:7]
	s_waitcnt vmcnt(0)

.LBB0_826:
	s_or_b64 exec, exec, s[4:5]
	s_mov_b64 s[4:5], exec
	v_mbcnt_lo_u32_b32 v2, s4, 0
	v_mbcnt_hi_u32_b32 v2, s5, v2
	v_cmp_eq_u32_e32 vcc, 0, v2
	s_waitcnt vmcnt(0)
	s_and_saveexec_b64 s[6:7], vcc
	s_cbranch_execz .LBB0_828
	s_bcnt1_i32_b64 s4, s[4:5]
	v_mov_b32_e32 v2, 0x2000
	v_mov_b32_e32 v3, s4
.LBB0_828:
	s_or_b64 exec, exec, s[6:7]
	s_waitcnt vmcnt(0)
